# barrier-shadow weight prefetch extended to G1 (both entry seams) and the G2 GLU tile
# baseline (speedup 1.0000x reference)
;     __host__ __device__ bool next(int i, Unit& u) const {
;         const long L = (long)i * G + c; if (L >= nwg) return false;
;         int wgid = (int)L; { const int q = nwg / NXCD, r = nwg % NXCD, xcd = wgid % NXCD, off = wgid / NXCD; wgid = (xcd < r ? xcd * (q + 1) : r * (q + 1) + (xcd - r) * q) + off; }
;         const int nig = WGM * nN, gid = wgid / nig, fm = gid * WGM, gsz = (nM - fm) < WGM ? (nM - fm) : WGM;
;         u.pm = fm + ((wgid % nig) % gsz); u.pn = (wgid % nig) / gsz; return true;
; __global__ void __launch_bounds__(512, 2) mk_fwd(Args a) {
;     ...
;     for (int l = 0; l < 2; ++l) {
;         const bf16_t* Wl = (const bf16_t*)(ws + WS_W) + (size_t)l * W_LAYER;
;         float* ss1 = ss + (size_t)(2 * l) * MTOK; float* ss2 = ss + (size_t)(2 * l + 1) * MTOK; float* ss1n = ss + (size_t)(2 * l + 2) * MTOK;
;         { pg8::Gemm g{bufA, Wl + W_IN, NTOK_P, INC - 256, DM}; pg8::StaticOrder S; S.init(NTOK_P, INC - 256, G, bx); EpiIn E{Z, ss1, a.in[I_BG] + l * 2048, 0};
;           pg8::gemm_phase<EpiIn, pg8::StaticOrder, true, true>(lds, g, S, E);
.LBB0_205:
	v_writelane_b32 v252, s88, 34
	s_nop 1
	v_writelane_b32 v252, s89, 35
	v_writelane_b32 v252, s66, 36
	s_nop 1
	v_writelane_b32 v252, s67, 37
	v_writelane_b32 v252, s72, 38
	s_nop 1
	v_writelane_b32 v252, s73, 39
	v_writelane_b32 v252, s74, 40
	v_writelane_b32 v252, s75, 41
	v_writelane_b32 v252, s76, 42
	v_writelane_b32 v252, s77, 43
	v_writelane_b32 v252, s78, 44
	v_writelane_b32 v252, s79, 45
	v_writelane_b32 v252, s80, 46
	v_writelane_b32 v252, s81, 47
	v_writelane_b32 v252, s82, 48
	v_writelane_b32 v252, s83, 49
	v_writelane_b32 v252, s84, 50
	v_writelane_b32 v252, s85, 51
	v_writelane_b32 v252, s86, 52
	v_writelane_b32 v252, s87, 53
	s_or_b64 exec, exec, s[0:1]
	s_add_u32 s36, s70, 0x5a00000
	s_addc_u32 s37, s71, 0
	s_add_u32 s40, s70, 0x6a80000
	s_addc_u32 s41, s71, 0
	s_add_u32 s48, s70, 0x7b00000
	s_addc_u32 s49, s71, 0
	s_add_u32 s50, s70, 0xe640000
	s_addc_u32 s51, s71, 0
	s_add_u32 s0, s70, 0xf6c0000
	s_addc_u32 s1, s71, 0
	v_writelane_b32 v252, s0, 54
	s_waitcnt vmcnt(2)
	v_and_b32_e32 v20, 7, v184
	v_mov_b32_e32 v1, 0
	v_writelane_b32 v252, s1, 55
	s_add_u32 s0, s70, 0x300000
	v_writelane_b32 v252, s0, 56
	s_addc_u32 s0, s71, 0
	s_cmpk_lt_i32 s2, 0x300
	v_writelane_b32 v252, s0, 57
	s_cselect_b64 s[0:1], -1, 0
	v_writelane_b32 v252, s0, 58
	s_ashr_i32 s33, s2, 31
	s_ashr_i32 s3, s34, 31
	v_writelane_b32 v252, s1, 59
	s_lshr_b32 s0, s33, 29
	s_add_i32 s0, s2, s0
	s_ashr_i32 s6, s0, 3
	s_and_b32 s0, s0, -8
	s_sub_i32 s0, s2, s0
	s_add_i32 s1, s34, s2
	s_add_u32 s28, s70, 0x4200
	s_addc_u32 s29, s71, 0
	s_add_u32 s46, s70, 0x4400
	s_addc_u32 s47, s71, 0
	s_add_u32 s4, s70, 0x4500
	s_addc_u32 s5, s71, 0
	v_writelane_b32 v252, s4, 60
	s_mul_i32 s13, s0, 17
	v_mov_b32_e32 v6, v1
	v_writelane_b32 v252, s5, 61
	s_add_u32 s4, s70, 0x4600
	s_addc_u32 s5, s71, 0
	v_writelane_b32 v252, s4, 62
	v_mov_b32_e32 v7, v1
	v_mov_b32_e32 v2, v1
	v_writelane_b32 v252, s5, 63
	s_add_u32 s4, s70, 0x4700
	s_addc_u32 s5, s71, 0
	v_writelane_b32 v253, s4, 0
	v_mov_b32_e32 v3, v1
	v_mov_b32_e32 v4, v1
	v_writelane_b32 v253, s5, 1
	s_add_u32 s4, s70, 0x4800
	s_addc_u32 s5, s71, 0
	v_writelane_b32 v253, s4, 2
	v_mov_b32_e32 v5, v1
	v_mbcnt_hi_u32_b32 v216, -1, v8
	v_writelane_b32 v253, s5, 3
	s_add_u32 s4, s70, 0x4900
	s_addc_u32 s5, s71, 0
	v_writelane_b32 v253, s4, 4
	s_mov_b32 s27, 0
	v_mov_b32_e32 v185, 0x358637bd
	v_writelane_b32 v253, s5, 5
	s_add_u32 s4, s70, 0x4a00
	s_addc_u32 s5, s71, 0
	v_writelane_b32 v253, s4, 6
	v_mov_b32_e32 v214, 0xc0135761
	v_mov_b32_e32 v215, 0x1a00
	v_writelane_b32 v253, s5, 7
	s_add_u32 s4, s70, 0x4b00
	s_addc_u32 s5, s71, 0
	v_writelane_b32 v253, s4, 8
	v_mov_b64_e32 v[212:213], 0x100
	v_mov_b64_e32 v[218:219], 0xff
	v_writelane_b32 v253, s5, 9
	s_add_u32 s4, s70, 0x4c00
	s_addc_u32 s5, s71, 0
	v_writelane_b32 v253, s4, 10
	s_movk_i32 s79, 0x200
	s_movk_i32 s80, 0x400
	v_writelane_b32 v253, s5, 11
	s_add_u32 s4, s70, 0x4d00
	s_addc_u32 s5, s71, 0
	v_writelane_b32 v253, s4, 12
	s_movk_i32 s81, 0x81
	s_mov_b32 s73, 0x10000
	v_writelane_b32 v253, s5, 13
	s_add_u32 s4, s70, 0x4e00
	s_addc_u32 s5, s71, 0
	v_writelane_b32 v253, s4, 14
	s_movk_i32 s84, 0x4000
	s_mov_b32 s85, 0x8000
	v_writelane_b32 v253, s5, 15
	s_add_u32 s4, s70, 0x4f00
	s_addc_u32 s5, s71, 0
	v_writelane_b32 v253, s4, 16
	s_mov_b32 s72, 0xc000
	s_mov_b32 s86, 0x800000
	v_writelane_b32 v253, s5, 17
	s_add_u32 s4, s70, 0x5000
	s_addc_u32 s5, s71, 0
	v_writelane_b32 v253, s4, 18
	s_movk_i32 s87, 0x1a00
	s_movk_i32 s88, 0x90
	v_writelane_b32 v253, s5, 19
	s_add_u32 s4, s70, 0x5100
	s_addc_u32 s5, s71, 0
	v_writelane_b32 v253, s4, 20
	s_movk_i32 s89, 0x4ff
	s_movk_i32 s90, 0x110
	v_writelane_b32 v253, s5, 21
	s_add_u32 s4, s70, 0x5200
	s_addc_u32 s5, s71, 0
	v_writelane_b32 v253, s4, 22
	s_movk_i32 s91, 0x210
	s_mov_b32 s92, 0xefa18f08
	v_writelane_b32 v253, s5, 23
	s_add_u32 s4, s70, 0x5300
	s_addc_u32 s5, s71, 0
	v_writelane_b32 v253, s4, 24
	s_mov_b32 s42, s27
	s_waitcnt lgkmcnt(0)
	v_writelane_b32 v253, s5, 25
	s_add_u32 s4, s70, 0x7400
	s_addc_u32 s5, s71, 0
	v_writelane_b32 v253, s4, 26
	s_nop 0
	v_writelane_b32 v253, s5, 27
	s_add_u32 s4, s70, 0x7500
	s_addc_u32 s5, s71, 0
	v_writelane_b32 v253, s4, 28
	s_cmpk_lt_i32 s2, 0x100
	s_nop 0
	v_writelane_b32 v253, s5, 29
	s_cselect_b64 s[4:5], -1, 0
	v_writelane_b32 v253, s4, 30
	s_nop 1
	v_writelane_b32 v253, s5, 31
	s_add_u32 s4, s68, 0x4200000
	s_addc_u32 s5, s69, 0
	v_writelane_b32 v253, s4, 32
	s_nop 1
	v_writelane_b32 v253, s5, 33
	s_add_u32 s4, s68, 0x4300000
	s_addc_u32 s5, s69, 0
	v_writelane_b32 v253, s4, 34
	s_nop 1
	v_writelane_b32 v253, s5, 35
	s_and_b32 s4, s62, 24
	s_add_u32 s8, s70, 0x180000
	s_addc_u32 s9, s71, 0
	v_writelane_b32 v253, s8, 36
	s_add_i32 s5, s94, s4
	s_add_u32 s4, s70, 0x200000
	v_writelane_b32 v253, s9, 37
	v_writelane_b32 v253, s4, 38
	s_addc_u32 s4, s71, 0
	v_writelane_b32 v253, s4, 39
	s_cmpk_lt_i32 s2, 0xe0
	s_mul_i32 s4, s94, 0x2100
	s_cselect_b64 s[8:9], -1, 0
	s_add_i32 s76, s4, 0
	s_mul_i32 s4, s94, 0xffffdf20
	v_writelane_b32 v253, s8, 40
	s_add_i32 s95, s76, s4
	s_add_u32 s4, s70, 0x1a0000
	v_writelane_b32 v253, s9, 41
	v_writelane_b32 v253, s4, 42
	s_addc_u32 s4, s71, 0
	v_writelane_b32 v253, s4, 43
	v_writelane_b32 v253, s5, 44
	s_lshl_b32 s4, s5, 4
	v_writelane_b32 v253, s4, 45
	s_mul_i32 s4, s94, 0x1100
	s_add_i32 s77, s4, 0
	s_add_i32 s77, s77, 0x14c00
	s_lshl_b32 s4, s94, 4
	s_cmpk_lt_i32 s2, 0x200
	v_writelane_b32 v253, s4, 46
	s_cselect_b64 s[4:5], -1, 0
	v_writelane_b32 v253, s4, 47
	s_lshl_b32 s10, s0, 4
	s_add_i32 s7, s1, 0xffffff80
	v_writelane_b32 v253, s5, 48
	s_and_b32 s4, s59, 0xffffffc0
	s_cmpk_lg_i32 s34, 0x100
	v_writelane_b32 v253, s4, 49
;     __host__ __device__ bool next(int i, Unit& u) const {
;         const long L = (long)i * G + c; if (L >= nwg) return false;
;         int wgid = (int)L; { const int q = nwg / NXCD, r = nwg % NXCD, xcd = wgid % NXCD, off = wgid / NXCD; wgid = (xcd < r ? xcd * (q + 1) : r * (q + 1) + (xcd - r) * q) + off; }
;         const int nig = WGM * nN, gid = wgid / nig, fm = gid * WGM, gsz = (nM - fm) < WGM ? (nM - fm) : WGM;
;         u.pm = fm + ((wgid % nig) % gsz); u.pn = (wgid % nig) / gsz; return true;
;     }
; template <class Epi, class Sched, bool ALIGN_EPI = false, bool SP2 = false>
; __device__ __forceinline__ void gemm_phase(PG8_LAS unsigned char* lds, const Gemm g, const Sched& S, const Epi& E) {
;     ...
;     const char* cA = (const char*)g.A + (size_t)cur.pm * tstep; const char* cB = (const char*)g.Bt + (size_t)cur.pn * tstep;
	s_cselect_b64 s[4:5], -1, 0
	v_writelane_b32 v253, s4, 50
	s_add_i32 s11, s2, 0x80
	s_nop 0
	v_writelane_b32 v253, s5, 51
	s_sub_i32 s5, s34, s2
	s_add_i32 s4, s5, 0xff
	s_cmpk_lt_i32 s2, 0x80
	s_cselect_b64 s[8:9], -1, 0
	v_cndmask_b32_e64 v0, 0, 1, s[8:9]
	v_writelane_b32 v253, s8, 52
	s_nop 1
	v_writelane_b32 v253, s9, 53
	s_and_b64 s[8:9], s[8:9], exec
	s_cselect_b32 s11, s11, -1
	s_add_i32 s12, s2, 0xffffff40
	s_add_u32 s8, s68, 0x4440000
	v_writelane_b32 v253, s8, 54
	s_addc_u32 s8, s69, 0
	v_writelane_b32 v253, s8, 55
	s_add_u32 s8, s68, 0x5440000
	v_writelane_b32 v253, s8, 56
	s_addc_u32 s8, s69, 0
	v_writelane_b32 v253, s8, 57
	s_add_u32 s8, s70, 0x7b00a00
	s_addc_u32 s9, s71, 0
	v_writelane_b32 v253, s8, 58
	s_nop 1
	v_writelane_b32 v253, s9, 59
	s_lshl_b32 s8, s0, 5
	s_add_u32 s14, s70, 0x7b01200
	s_addc_u32 s15, s71, 0
	v_writelane_b32 v253, s14, 60
	s_cmpk_lt_i32 s2, 0x400
	s_nop 0
	v_writelane_b32 v253, s15, 61
	s_cselect_b64 s[14:15], -1, 0
	s_lshl_b32 s9, s0, 7
	s_cmp_lt_i32 s0, 0
	s_cselect_b32 s10, s13, s10
	s_mul_i32 s13, s0, 33
	s_cselect_b32 s13, s13, s8
	s_movk_i32 s8, 0x61
	s_cselect_b32 s8, s8, 0x60
	v_writelane_b32 v253, s14, 62
	s_mul_i32 s8, s0, s8
	s_mulk_i32 s0, 0x81
	v_writelane_b32 v253, s15, 63
	s_cselect_b32 s14, s0, s9
	s_add_i32 s8, s8, s6
	s_mul_hi_i32 s0, s8, 0x2aaaaaab
	s_lshr_b32 s9, s0, 31
	s_ashr_i32 s0, s0, 4
	s_add_i32 s0, s0, s9
	s_mul_i32 s9, s0, 0x60
	s_sub_i32 s8, s8, s9
	s_bfe_i32 s9, s8, 0x80000
	s_bfe_u32 s9, s9, 0x3000c
	s_add_i32 s9, s8, s9
	s_and_b32 s15, s9, 0xf8
	s_add_i32 s10, s10, s6
	s_sub_i32 s8, s8, s15
	s_ashr_i32 s15, s10, 31
	s_lshr_b32 s15, s15, 28
	s_add_i32 s15, s10, s15
	s_and_b32 s16, s15, 0xfff0
	s_sub_i32 s10, s10, s16
	s_bfe_i32 s16, s10, 0x80000
	s_bfe_u32 s16, s16, 0x3000c
	s_add_i32 s16, s10, s16
	s_and_b32 s17, s16, 0xf8
	s_lshl_b32 s0, s0, 3
	s_sext_i32_i8 s8, s8
	s_sub_i32 s10, s10, s17
	s_bfe_i32 s9, s9, 0x80000
	s_add_i32 s18, s0, s8
	s_ashr_i32 s0, s15, 4
	s_bfe_i32 s8, s16, 0x80000
	s_sext_i32_i16 s17, s9
	s_lshl_b32 s0, s0, 3
	s_sext_i32_i16 s8, s8
	s_sext_i32_i8 s9, s10
	s_add_i32 s20, s0, s9
	s_ashr_i32 s0, s8, 3
	v_writelane_b32 v254, s0, 0
	s_lshr_b32 s0, s8, 3
	s_bfe_i64 s[8:9], s[0:1], 0x100000
	s_lshl_b64 s[8:9], s[8:9], 18
	v_writelane_b32 v254, s8, 1
	s_ashr_i32 s0, s17, 3
	s_ashr_i32 s21, s20, 31
	v_writelane_b32 v254, s9, 2
	v_writelane_b32 v254, s0, 3
	s_mov_b32 s8, s20
	v_writelane_b32 v254, s8, 4
	s_lshr_b32 s0, s17, 3
	s_nop 0
	v_writelane_b32 v254, s9, 5
	s_lshl_b64 s[8:9], s[20:21], 18
	s_add_u32 s8, s40, s8
	s_addc_u32 s9, s41, s9
	s_add_u32 s16, s8, 0x20000
	v_writelane_b32 v254, s8, 6
	s_addc_u32 s17, s9, 0
	s_cmpk_gt_i32 s2, 0xbf
	v_writelane_b32 v254, s9, 7
	v_writelane_b32 v254, s16, 8
	s_cselect_b32 s8, s12, s11
	s_nop 0
	v_writelane_b32 v254, s17, 9
	v_writelane_b32 v254, s8, 10
	v_readfirstlane_b32 s8, v0
	s_cselect_b32 s8, 2, s8
	v_cvt_f32_u32_e32 v0, s34
	v_writelane_b32 v254, s8, 11
	s_cselect_b32 s8, 64, 1
	v_writelane_b32 v254, s8, 12
	s_add_i32 s8, s13, s6
	s_ashr_i32 s9, s8, 31
	s_lshr_b32 s9, s9, 27
	s_add_i32 s9, s8, s9
	s_and_b32 s10, s9, 0xffe0
	s_sub_i32 s8, s8, s10
	s_bfe_i32 s10, s8, 0x80000
	s_bfe_u32 s10, s10, 0x3000c
	s_add_i32 s10, s8, s10
	s_and_b32 s11, s10, 0xf8
	s_sub_i32 s8, s8, s11
	s_ashr_i32 s9, s9, 5
	s_bfe_i32 s10, s10, 0x80000
	s_lshl_b32 s9, s9, 3
	s_sext_i32_i16 s10, s10
	s_sext_i32_i8 s8, s8
	s_add_i32 s16, s9, s8
	s_ashr_i32 s8, s10, 3
	v_writelane_b32 v254, s8, 13
	s_lshr_b32 s8, s10, 3
	s_bfe_i64 s[8:9], s[8:9], 0x100000
	s_ashr_i32 s17, s16, 31
	s_lshl_b64 s[12:13], s[8:9], 18
	s_lshl_b64 s[10:11], s[16:17], 18
	v_writelane_b32 v254, s12, 14
	v_rcp_iflag_f32_e32 v0, v0
	s_nop 0
	v_writelane_b32 v254, s13, 15
	s_add_u32 s12, s36, s10
	s_addc_u32 s13, s37, s11
	s_add_u32 s20, s12, 0x20000
	v_writelane_b32 v254, s12, 16
	s_addc_u32 s21, s13, 0
	s_add_u32 s10, s50, s10
	v_writelane_b32 v254, s13, 17
	v_writelane_b32 v254, s20, 18
	s_addc_u32 s11, s51, s11
	s_add_u32 s12, s10, 0x20000
	v_writelane_b32 v254, s21, 19
	v_writelane_b32 v254, s10, 20
	s_addc_u32 s13, s11, 0
	s_add_i32 s6, s14, s6
	v_writelane_b32 v254, s11, 21
	s_ashr_i32 s10, s6, 31
	s_lshr_b32 s10, s10, 25
	s_add_i32 s10, s6, s10
	s_and_b32 s11, s10, 0xff80
	s_sub_i32 s6, s6, s11
	s_bfe_i32 s11, s6, 0x80000
	s_bfe_u32 s11, s11, 0x3000c
	v_writelane_b32 v254, s12, 22
	s_add_i32 s11, s6, s11
	s_ashr_i32 s10, s10, 7
	v_writelane_b32 v254, s13, 23
	s_and_b32 s12, s11, 0xf8
	s_sub_i32 s6, s6, s12
	s_bfe_i32 s11, s11, 0x80000
	s_lshl_b32 s10, s10, 3
	s_sext_i32_i16 s11, s11
	s_sext_i32_i8 s6, s6
	s_add_i32 s12, s10, s6
	s_ashr_i32 s6, s11, 3
	v_writelane_b32 v254, s6, 24
	s_lshr_b32 s6, s11, 3
	s_bfe_i64 s[10:11], s[6:7], 0x100000
	s_lshl_b64 s[10:11], s[10:11], 19
	s_ashr_i32 s13, s12, 31
	v_writelane_b32 v254, s10, 25
	s_mov_b32 s6, s12
	v_mul_f32_e32 v0, 0x4f7ffffe, v0
	v_writelane_b32 v254, s11, 26
	s_lshl_b64 s[10:11], s[12:13], 19
	v_writelane_b32 v254, s6, 27
	s_add_u32 s10, s36, s10
	s_addc_u32 s11, s37, s11
	v_writelane_b32 v254, s7, 28
	s_add_u32 s12, s10, 0x40000
	v_writelane_b32 v254, s10, 29
	s_addc_u32 s13, s11, 0
	s_ashr_i32 s19, s18, 31
	v_writelane_b32 v254, s11, 30
	v_writelane_b32 v254, s12, 31
	s_bfe_i64 s[10:11], s[0:1], 0x100000
	s_lshl_b64 s[10:11], s[10:11], 19
	v_writelane_b32 v254, s13, 32
	v_writelane_b32 v254, s10, 33
	s_mov_b32 s0, s18
	v_cvt_u32_f32_e32 v0, v0
	v_writelane_b32 v254, s11, 34
	s_lshl_b64 s[10:11], s[18:19], 19
	v_writelane_b32 v254, s0, 35
; #define LAS __attribute__((address_space(3)))
; __device__ __forceinline__ int opq(int v) { asm volatile("" : "+v"(v)); return v; }
; template <int CT, class Epi> __device__ __forceinline__ void skinny_gemm(LAS unsigned char* lds, const bf16_t* A, const bf16_t* Bt, int N, int K, const Epi& E, int first) {
;     const int tid = opq(threadIdx.x), lane = tid & 63, wave = __builtin_amdgcn_readfirstlane(tid >> 6), r = lane & 15, qd = lane >> 4;
;     const int G = gridDim.x, nunits = 8 * (N / (16 * CT)), kw = K / 8, nsteps = kw / 32;
;     LAS float* red = (LAS float*)lds;
;     for (int u = (int)((blockIdx.x + G - first % G) % G); u < nunits; u += G) {
; __global__ void __launch_bounds__(512, 2) mk_fwd(Args a) {
;     ...
;         { int u0 = -1, un = 0, us = 1;
;           if (G == 256) { if (bx >= 192) { u0 = bx - 192; un = 2; us = 64; } else if (bx < 128) { u0 = 128 + bx; un = 1; } }
;           else { u0 = bx; un = (2 * DEC_B - bx + G - 1) / G; us = G; }
	s_add_u32 s10, s30, s10
	s_addc_u32 s11, s31, s11
	v_writelane_b32 v254, s1, 36
	s_add_u32 s12, s10, 0x40000
	v_writelane_b32 v254, s10, 37
	s_addc_u32 s13, s11, 0
	s_mov_b32 s0, s16
	v_writelane_b32 v254, s11, 38
	v_writelane_b32 v254, s12, 39
	s_lshl_b64 s[10:11], s[16:17], 19
	v_readfirstlane_b32 s6, v0
	v_writelane_b32 v254, s13, 40
	s_lshl_b64 s[12:13], s[8:9], 19
	v_writelane_b32 v254, s12, 41
	s_add_u32 s10, s68, s10
	s_addc_u32 s11, s69, s11
	v_writelane_b32 v254, s13, 42
	s_add_u32 s12, s10, 0x40000
	v_writelane_b32 v254, s10, 43
	s_addc_u32 s13, s11, 0
	s_lshl_b64 s[8:9], s[8:9], 21
	v_writelane_b32 v254, s11, 44
	v_writelane_b32 v254, s12, 45
	s_mov_b64 s[20:21], 0x80
	s_nop 0
	v_writelane_b32 v254, s13, 46
	v_writelane_b32 v254, s8, 47
	s_nop 1
	v_writelane_b32 v254, s9, 48
	s_lshl_b64 s[8:9], s[16:17], 21
	s_add_u32 s8, s48, s8
	v_writelane_b32 v254, s0, 49
	s_addc_u32 s9, s49, s9
	s_add_u32 s10, s8, 0x100000
	v_writelane_b32 v254, s1, 50
	v_writelane_b32 v254, s8, 51
	s_addc_u32 s11, s9, 0
	s_sub_i32 s0, 0, s34
	s_mul_i32 s0, s0, s6
	s_mul_hi_u32 s0, s6, s0
	s_add_i32 s6, s6, s0
	s_mul_hi_u32 s0, s1, s6
	s_mul_i32 s0, s0, s34
	s_sub_i32 s0, s1, s0
	v_writelane_b32 v254, s9, 52
	s_sub_i32 s8, s0, s34
	s_cmp_ge_u32 s0, s34
	s_cselect_b32 s0, s8, s0
	s_sub_i32 s8, s0, s34
	v_writelane_b32 v254, s10, 53
	s_cmp_ge_u32 s0, s34
	s_nop 0
	v_writelane_b32 v254, s11, 54
	s_cselect_b32 s11, s8, s0
	s_cmpk_lt_i32 s11, 0x1a0
	s_cselect_b64 s[8:9], -1, 0
	s_abs_i32 s0, s34
	v_cvt_f32_u32_e32 v0, s0
	v_writelane_b32 v254, s8, 55
	v_rcp_iflag_f32_e32 v0, v0
	s_nop 0
	v_writelane_b32 v254, s9, 56
	s_sub_i32 s8, 0, s0
	v_mul_f32_e32 v0, 0x4f7ffffe, v0
	v_cvt_u32_f32_e32 v0, v0
	s_nop 0
	v_readfirstlane_b32 s9, v0
	s_mul_i32 s8, s8, s9
	s_mul_hi_u32 s8, s9, s8
	s_add_i32 s9, s9, s8
	s_abs_i32 s8, s7
	s_mul_hi_u32 s10, s8, s9
	s_mul_i32 s10, s10, s0
	s_sub_i32 s8, s8, s10
	s_ashr_i32 s7, s7, 31
	s_sub_i32 s10, s8, s0
	s_cmp_ge_u32 s8, s0
	s_cselect_b32 s8, s10, s8
	s_sub_i32 s10, s8, s0
	s_cmp_ge_u32 s8, s0
	s_cselect_b32 s8, s10, s8
	s_xor_b32 s8, s8, s7
	s_sub_i32 s8, s8, s7
	s_cmp_lt_i32 s8, 64
	s_cselect_b64 s[12:13], -1, 0
	v_writelane_b32 v254, s12, 57
	s_ashr_i32 s7, s8, 31
	v_mov_b32_e32 v0, v1
	v_writelane_b32 v254, s13, 58
	v_writelane_b32 v254, s7, 59
	s_lshr_b32 s7, s7, 29
	s_add_i32 s7, s8, s7
	s_ashr_i32 s10, s7, 3
	v_writelane_b32 v254, s10, 60
	s_and_b32 s7, s7, -8
	v_writelane_b32 v254, s8, 61
	s_sub_i32 s7, s8, s7
	s_mul_hi_u32 s8, s9, 0xc0
	s_cmp_gt_i32 s7, -1
	s_mul_i32 s8, s8, s0
	s_cselect_b64 s[12:13], -1, 0
	s_sub_i32 s8, 0xc0, s8
	s_lshl_b32 s10, s7, 3
	v_writelane_b32 v255, s10, 0
	s_sub_i32 s10, s8, s0
	s_cmp_ge_u32 s8, s0
	s_cselect_b32 s8, s10, s8
	s_sub_i32 s10, s8, s0
	s_cmp_ge_u32 s8, s0
	s_cselect_b32 s8, s10, s8
	s_sub_i32 s1, s1, s8
	s_mul_hi_u32 s6, s1, s6
	s_mul_i32 s6, s6, s34
	s_sub_i32 s1, s1, s6
	s_sub_i32 s6, s1, s34
	s_cmp_ge_u32 s1, s34
	s_cselect_b32 s1, s6, s1
	s_sub_i32 s6, s1, s34
	s_cmp_ge_u32 s1, s34
	s_cselect_b32 s10, s6, s1
	v_writelane_b32 v254, s12, 62
	s_cmpk_lt_i32 s10, 0x80
	v_mov_b64_e32 v[18:19], v[6:7]
	v_writelane_b32 v254, s13, 63
	s_cselect_b64 s[12:13], -1, 0
	s_sub_i32 s1, 0xffffff01, s5
	s_max_i32 s1, s4, s1
	s_mul_hi_u32 s5, s1, s9
	s_mul_i32 s6, s5, s0
	s_sub_i32 s1, s1, s6
	s_xor_b32 s4, s4, s34
	s_ashr_i32 s4, s4, 31
	s_add_i32 s6, s5, 1
	s_sub_i32 s8, s1, s0
	s_cmp_ge_u32 s1, s0
	s_cselect_b32 s5, s6, s5
	s_cselect_b32 s1, s8, s1
	s_add_i32 s6, s5, 1
	v_writelane_b32 v255, s12, 1
	s_cmp_ge_u32 s1, s0
	s_mul_i32 s0, s35, s34
	v_writelane_b32 v255, s13, 2
	s_mul_i32 s0, s0, s58
	v_writelane_b32 v255, s0, 3
	s_cselect_b32 s0, s6, s5
	s_xor_b32 s0, s0, s4
	s_sub_i32 s0, s0, s4
	v_writelane_b32 v255, s0, 4
	s_mul_i32 s0, s7, 9
	s_cmpk_lt_i32 s11, 0x100
	v_writelane_b32 v255, s0, 5
	s_cselect_b64 s[0:1], -1, 0
	v_writelane_b32 v255, s0, 6
	s_cmpk_lt_i32 s11, 0x200
	v_mov_b64_e32 v[16:17], v[4:5]
	v_writelane_b32 v255, s1, 7
	s_cselect_b64 s[0:1], -1, 0
	v_writelane_b32 v255, s0, 8
	s_lshl_b32 s82, s34, 6
	v_mov_b64_e32 v[14:15], v[2:3]
	v_writelane_b32 v255, s1, 9
	s_lshl_b32 s0, s94, 5
	s_add_i32 s78, s0, 0
	s_lshl_b32 s0, s11, 3
	v_writelane_b32 v255, s0, 10
	s_lshl_b32 s0, s11, 6
	v_writelane_b32 v255, s0, 11
	s_add_u32 s0, s70, 0x6a80800
	v_writelane_b32 v255, s0, 12
	s_addc_u32 s0, s71, 0
	v_writelane_b32 v255, s0, 13
	s_lshl_b32 s0, s10, 2
	v_writelane_b32 v255, s0, 14
	v_writelane_b32 v255, s10, 15
	s_lshl_b32 s0, s10, 6
	v_writelane_b32 v255, s0, 16
	v_writelane_b32 v255, s11, 17
	s_lshl_b32 s0, s11, 2
	v_writelane_b32 v255, s0, 18
	s_add_i32 s0, 0, 0x23fc0
	v_writelane_b32 v255, s0, 19
	s_add_i32 s0, 0, 0x23fc4
	v_writelane_b32 v255, s0, 20
	s_add_i32 s0, 0, 0x11810
	v_writelane_b32 v255, s0, 21
	s_add_i32 s0, 0, 0x9000
	v_writelane_b32 v255, s0, 22
	v_cmp_eq_u32_e64 s[0:1], 0, v20
	v_mov_b64_e32 v[12:13], v[0:1]
	v_mov_b64_e32 v[10:11], v[6:7]
	v_writelane_b32 v255, s0, 23
	v_mov_b64_e32 v[8:9], v[4:5]
	v_mov_b64_e32 v[6:7], v[2:3]
	v_writelane_b32 v255, s1, 24
	s_mov_b64 s[0:1], -1
	v_writelane_b32 v255, s0, 25
	v_mov_b64_e32 v[4:5], v[0:1]
	s_lshl_b32 s83, s34, 2
	v_writelane_b32 v255, s1, 26
	v_writelane_b32 v255, s96, 27
	s_mov_b32 s35, 0x18000
	s_nop 0
	v_writelane_b32 v255, s97, 28
	v_writelane_b32 v255, s94, 29
	v_writelane_b32 v255, s28, 30
	s_nop 1
	v_writelane_b32 v255, s29, 31
	v_writelane_b32 v255, s95, 32
	v_writelane_b32 v255, s46, 33
	s_nop 1
	v_writelane_b32 v255, s47, 34
	s_branch .LBB0_209

; #define PG8_WAIT_V(n) asm volatile("s_waitcnt vmcnt(" #n ")" ::: "memory")
; template <class Epi, class Sched, bool ALIGN_EPI = false, bool SP2 = false>
; __device__ __forceinline__ void gemm_phase(PG8_LAS unsigned char* lds, const Gemm g, const Sched& S, const Epi& E) {
;     ...
;     for (int i = 0; i < 2; ++i) { int R, C; stage_rc(tid * 16 + i * 8192, R, C); const int Rb = Epi::PERM ? ((R & ~31) + perm32(R & 31)) : R;
;         voffA[i] = (unsigned)(R * K + C) * 2u; voffB[i] = (unsigned)(Rb * K + C) * 2u; }
;     const size_t kstep = (size_t)(BK * 2);
;     const size_t hstep = (size_t)HALF * K * 2;
;     const size_t tstep = 2 * hstep;
;     const unsigned ldsw = (unsigned)wid * 1024u;
;     const int aoff = lds_byte(wr * 64 + fr, fq * 8), boff = lds_byte(wc * 32 + fr, fq * 8);
;     ...
;     Unit cur, nxt; int ui = 0;
;     if (!S.next(0, cur)) return;
;     f32x4 acc[2][2][4][2];
; #pragma unroll
;     for (int a = 0; a < 2; ++a)
; #pragma unroll
;         for (int b = 0; b < 2; ++b)
; #pragma unroll
;             for (int m = 0; m < 4; ++m)
; #pragma unroll
;                 for (int n = 0; n < 2; ++n) acc[a][b][m][n] = (f32x4){0.f, 0.f, 0.f, 0.f};
;     bf16x8 At[4][2], B0[2][2], B1[2][2];
;     const char* cA = (const char*)g.A + (size_t)cur.pm * tstep; const char* cB = (const char*)g.Bt + (size_t)cur.pn * tstep;
;     S.a_ready(cur);
;     if constexpr (SP2) {
;         PG8_STAGE(PG8_SB(0, 0), cB, voffB); PG8_STAGE(PG8_SB(0, 1), cB + hstep, voffB); PG8_STAGE(PG8_SA(0, 0), cA, voffA); PG8_STAGE(PG8_SA(0, 1), cA + hstep, voffA);
;         if (wr == 1) PG8_BAR;
;         PG8_WAIT_V(2); PG8_BAR;
;         PG8_STAGE(PG8_SB(1, 0), cB + kstep, voffB); PG8_STAGE(PG8_SA(1, 0), cA + kstep, voffA); PG8_STAGE(PG8_SB(1, 1), cB + hstep + kstep, voffB);
;         PG8_WAIT_V(6); PG8_BAR;
; __global__ void __launch_bounds__(512, 2) mk_fwd(Args a) {
;     ...
;     for (int l = 0; l < 2; ++l) {
;         const bf16_t* Wl = (const bf16_t*)(ws + WS_W) + (size_t)l * W_LAYER;
;         float* ss1 = ss + (size_t)(2 * l) * MTOK; float* ss2 = ss + (size_t)(2 * l + 1) * MTOK; float* ss1n = ss + (size_t)(2 * l + 2) * MTOK;
;         { pg8::Gemm g{bufA, Wl + W_IN, NTOK_P, INC - 256, DM}; pg8::StaticOrder S; S.init(NTOK_P, INC - 256, G, bx); EpiIn E{Z, ss1, a.in[I_BG] + l * 2048, 0};
;           pg8::gemm_phase<EpiIn, pg8::StaticOrder, true, true>(lds, g, S, E);
.LBB0_207:
	s_or_b64 exec, exec, s[0:1]
	s_mov_b64 s[0:1], 0
	s_waitcnt lgkmcnt(0)
.LBB0_208:
	s_mov_b64 s[4:5], 0
	v_writelane_b32 v255, s4, 25
	s_mov_b32 s42, 1
	s_and_b64 vcc, exec, s[0:1]
	v_writelane_b32 v255, s5, 26
	s_cbranch_vccnz .LBB0_1092
.LBB0_209:
	s_mul_i32 s4, s42, 0x1b00000
	s_mov_b32 s5, s27
	v_readlane_b32 s0, v252, 56
	v_writelane_b32 v255, s4, 35
	s_add_u32 s0, s0, s4
	s_mul_i32 s26, s42, 0x8400
	v_writelane_b32 v255, s5, 36
	v_writelane_b32 v255, s0, 37
	v_readlane_b32 s0, v252, 57
	s_addc_u32 s0, s0, 0
	v_readlane_b32 s4, v252, 34
	v_writelane_b32 v255, s0, 38
	s_lshl_b64 s[0:1], s[26:27], 2
	v_readlane_b32 s5, v252, 35
	s_add_u32 s38, s4, s0
	s_addc_u32 s39, s5, s1
	s_lshl_b32 s26, s42, 11
	s_lshl_b64 s[0:1], s[26:27], 2
	v_readlane_b32 s4, v252, 38
	s_mov_b64 s[46:47], s[40:41]
	v_readlane_b32 s5, v252, 39
	s_add_u32 s40, s4, s0
	s_addc_u32 s41, s5, s1
	v_readlane_b32 s0, v252, 58
	v_mov_b32_e32 v20, v184
	v_readlane_b32 s1, v252, 59
	s_andn2_b64 vcc, exec, s[0:1]
	v_readfirstlane_b32 s4, v20
	v_readlane_b32 s6, v252, 40
	v_readlane_b32 s7, v252, 41
	v_readlane_b32 s8, v252, 42
	v_readlane_b32 s9, v252, 43
	v_readlane_b32 s10, v252, 44
	v_readlane_b32 s11, v252, 45
	v_readlane_b32 s12, v252, 46
	v_readlane_b32 s13, v252, 47
	v_readlane_b32 s14, v252, 48
	v_readlane_b32 s15, v252, 49
	v_readlane_b32 s16, v252, 50
	v_readlane_b32 s17, v252, 51
	v_readlane_b32 s18, v252, 52
	v_readlane_b32 s19, v252, 53
	s_cbranch_vccz .Lbsh_g1_go
	s_barrier
	s_branch .LBB0_265
.Lbsh_g1_go:
	v_lshlrev_b32_e32 v0, 4, v20
	v_add_u32_e32 v2, 0x2000, v0
	v_ashrrev_i32_e32 v3, 31, v2
	v_lshrrev_b32_e32 v3, 22, v3
	v_add_u32_e32 v3, v2, v3
	v_ashrrev_i32_e32 v21, 10, v3
	v_mul_i32_i24_e32 v3, 0x400, v21
	v_sub_u32_e32 v2, v2, v3
	v_lshrrev_b32_e32 v3, 4, v2
	v_bitop3_b32 v2, v3, v2, 32 bitop3:0x6c
	v_ashrrev_i32_e32 v3, 31, v2
	v_lshrrev_b32_e32 v3, 26, v3
	v_add_u32_e32 v3, v2, v3
	v_lshlrev_b32_e32 v23, 3, v21
	v_ashrrev_i32_e32 v22, 6, v3
	v_and_b32_e32 v23, -16, v23
	s_waitcnt vmcnt(1)
	v_add_u32_e32 v24, v22, v23
	v_and_b32_e32 v23, 3, v22
	s_mov_b32 s0, 0x1fffe0
	s_waitcnt lgkmcnt(0)
	v_lshrrev_b32_e32 v25, 2, v24
	v_lshlrev_b32_e32 v26, 1, v24
	v_and_b32_e32 v3, 0xc0, v3
	v_and_or_b32 v23, v24, s0, v23
	v_and_b32_e32 v25, 4, v25
	v_and_b32_e32 v26, 24, v26
	v_sub_u32_e32 v2, v2, v3
	s_waitcnt vmcnt(0)
	v_mov_b32_e32 v30, 1
	v_or3_b32 v25, v23, v25, v26
	v_lshlrev_b32_e32 v23, 5, v21
	v_ashrrev_i16_sdwa v2, v30, sext(v2) dst_sel:DWORD dst_unused:UNUSED_PAD src0_sel:DWORD src1_sel:BYTE_0
	v_and_b32_e32 v26, 32, v23
	v_bfe_i32 v23, v2, 0, 16
	v_add_lshl_u32 v3, v26, v23, 1
	v_lshl_add_u32 v2, v25, 11, v3
	v_lshl_add_u32 v164, v24, 11, v3
	v_bfe_i32 v3, v20, 27, 1
	v_lshrrev_b32_e32 v3, 22, v3
	v_add_u32_e32 v3, v0, v3
	v_and_b32_e32 v3, 0xfffffc00, v3
	v_sub_u32_e32 v0, v0, v3
	v_lshrrev_b32_e32 v3, 4, v0
	v_ashrrev_i32_e32 v25, 31, v20
	v_bitop3_b32 v0, v3, v0, 32 bitop3:0x6c
	v_lshrrev_b32_e32 v25, 26, v25
	v_ashrrev_i32_e32 v3, 31, v0
	v_add_u32_e32 v25, v20, v25
	v_lshrrev_b32_e32 v3, 26, v3
	v_ashrrev_i32_e32 v25, 6, v25
	v_add_u32_e32 v3, v0, v3
	v_lshlrev_b32_e32 v26, 3, v25
	v_ashrrev_i32_e32 v24, 6, v3
	v_and_b32_e32 v26, -16, v26
	v_add_u32_e32 v27, v24, v26
	v_and_b32_e32 v26, 3, v24
	v_lshrrev_b32_e32 v28, 2, v27
	v_lshlrev_b32_e32 v29, 1, v27
	v_and_b32_e32 v3, 0xc0, v3
	s_ashr_i32 s6, s4, 6
	v_and_or_b32 v26, v27, s0, v26
	v_and_b32_e32 v28, 4, v28
	v_and_b32_e32 v29, 24, v29
	v_sub_u32_e32 v0, v0, v3
	s_ashr_i32 s5, s4, 8
	s_lshl_b32 s26, s6, 10
	v_or3_b32 v28, v26, v28, v29
	v_lshlrev_b32_e32 v26, 5, v25
	v_ashrrev_i16_sdwa v0, v30, sext(v0) dst_sel:DWORD dst_unused:UNUSED_PAD src0_sel:DWORD src1_sel:BYTE_0
	v_readlane_b32 s0, v254, 33
	v_readlane_b32 s7, v255, 37
	v_and_b32_e32 v29, 32, v26
	v_bfe_i32 v26, v0, 0, 16
	v_readlane_b32 s1, v254, 34
	s_add_u32 s0, s7, s0
	v_readlane_b32 s7, v255, 38
	v_add_lshl_u32 v3, v29, v26, 1
	s_addc_u32 s1, s7, s1
	s_add_i32 s54, s26, 0
	v_lshl_add_u32 v0, v28, 11, v3
	s_add_i32 m0, s54, 0x10000
	v_lshl_add_u32 v166, v27, 11, v3
	global_load_lds_dwordx4 v0, s[0:1]
	s_add_i32 m0, s54, 0x12000
	s_add_u32 s8, s0, 0x40000
	global_load_lds_dwordx4 v2, s[0:1]
	s_addc_u32 s9, s1, 0
	s_add_i32 m0, s54, 0x14000
	s_add_i32 s55, s54, 0x2000
	global_load_lds_dwordx4 v0, s[8:9]
	s_add_i32 m0, s54, 0x16000
	s_add_i32 s58, s54, 0x4000
	global_load_lds_dwordx4 v2, s[8:9]
	v_readlane_b32 s8, v254, 37
	s_barrier
	s_mov_b32 m0, s54
	v_readlane_b32 s9, v254, 38
	s_add_i32 s59, s54, 0x6000
	s_cmp_eq_u32 s5, 1
	s_nop 2
	global_load_lds_dwordx4 v166, s[8:9]
	s_mov_b32 m0, s55
	s_nop 0
	global_load_lds_dwordx4 v164, s[8:9]
	v_readlane_b32 s8, v254, 39
	s_mov_b32 m0, s58
	v_readlane_b32 s9, v254, 40
	s_nop 4
	global_load_lds_dwordx4 v166, s[8:9]
	s_mov_b32 m0, s59
	s_nop 0
	global_load_lds_dwordx4 v164, s[8:9]
	s_cselect_b64 s[8:9], -1, 0
	s_cmp_lg_u32 s5, 1
	s_cbranch_scc1 .LBB0_212
	s_barrier

; #define PG8_STAGE(bufoff, gbase, voff) do { _Pragma("unroll") for (int _i = 0; _i < 2; ++_i) \
;         __builtin_amdgcn_global_load_lds((const unsigned*)((const char*)(gbase) + (voff)[_i]), (PG8_LAS unsigned*)(lds + (bufoff) + ldsw + _i * 8192), 16, 0, 0); } while (0)
; #define PG8_WAIT_V(n) asm volatile("s_waitcnt vmcnt(" #n ")" ::: "memory")
; template <class Epi, class Sched, bool ALIGN_EPI = false, bool SP2 = false>
; __device__ __forceinline__ void gemm_phase(PG8_LAS unsigned char* lds, const Gemm g, const Sched& S, const Epi& E) {
;     ...
;     for (int i = 0; i < 2; ++i) { int R, C; stage_rc(tid * 16 + i * 8192, R, C); const int Rb = Epi::PERM ? ((R & ~31) + perm32(R & 31)) : R;
;         voffA[i] = (unsigned)(R * K + C) * 2u; voffB[i] = (unsigned)(Rb * K + C) * 2u; }
;     const size_t kstep = (size_t)(BK * 2);
;     const size_t hstep = (size_t)HALF * K * 2;
;     const size_t tstep = 2 * hstep;
;     const unsigned ldsw = (unsigned)wid * 1024u;
;     const int aoff = lds_byte(wr * 64 + fr, fq * 8), boff = lds_byte(wc * 32 + fr, fq * 8);
;     ...
;     Unit cur, nxt; int ui = 0;
;     if (!S.next(0, cur)) return;
;     f32x4 acc[2][2][4][2];
; #pragma unroll
;     for (int a = 0; a < 2; ++a)
; #pragma unroll
;         for (int b = 0; b < 2; ++b)
; #pragma unroll
;             for (int m = 0; m < 4; ++m)
; #pragma unroll
;                 for (int n = 0; n < 2; ++n) acc[a][b][m][n] = (f32x4){0.f, 0.f, 0.f, 0.f};
;     bf16x8 At[4][2], B0[2][2], B1[2][2];
;     const char* cA = (const char*)g.A + (size_t)cur.pm * tstep; const char* cB = (const char*)g.Bt + (size_t)cur.pn * tstep;
;     S.a_ready(cur);
;     if constexpr (SP2) {
;         PG8_STAGE(PG8_SB(0, 0), cB, voffB); PG8_STAGE(PG8_SB(0, 1), cB + hstep, voffB); PG8_STAGE(PG8_SA(0, 0), cA, voffA); PG8_STAGE(PG8_SA(0, 1), cA + hstep, voffA);
;         if (wr == 1) PG8_BAR;
;         PG8_WAIT_V(2); PG8_BAR;
;         PG8_STAGE(PG8_SB(1, 0), cB + kstep, voffB); PG8_STAGE(PG8_SA(1, 0), cA + kstep, voffA); PG8_STAGE(PG8_SB(1, 1), cB + hstep + kstep, voffB);
;         PG8_WAIT_V(6); PG8_BAR;
; __global__ void __launch_bounds__(512, 2) mk_fwd(Args a) {
;     ...
;         { pg8::Gemm g{ssmy, Wl + W_GLU, NTOK_P, 512, 512}; pg8::StaticOrder S; S.init(NTOK_P, 512, G, bx); EpiGlu E{ssmy, ssmg, a.in[I_BGLU] + l * 512};
;           pg8::gemm_phase<EpiGlu, pg8::StaticOrder, true, true>(lds, g, S, E);
.LBB0_546:
	s_or_b64 exec, exec, s[0:1]
	v_readlane_b32 s0, v255, 37
	v_readlane_b32 s4, v252, 16
	s_add_u32 s26, s0, 0x680000
	v_readlane_b32 s0, v255, 38
	s_mov_b32 s25, s27
	v_readlane_b32 s10, v252, 22
	v_readlane_b32 s11, v252, 23
	v_readlane_b32 s14, v252, 26
	v_readlane_b32 s15, v252, 27
	s_addc_u32 s74, s0, 0
	s_lshl_b64 s[0:1], s[24:25], 2
	v_readlane_b32 s8, v252, 20
	s_mov_b64 s[10:11], s[14:15]
	v_readlane_b32 s9, v252, 21
	s_add_u32 s8, s10, s0
	s_addc_u32 s9, s11, s1
	v_readlane_b32 s0, v253, 52
	v_readlane_b32 s6, v252, 18
	v_mov_b32_e32 v20, v184
	v_readlane_b32 s1, v253, 53
	s_waitcnt lgkmcnt(0)
	s_and_b64 vcc, s[0:1], exec
	v_readfirstlane_b32 s6, v20
	v_readlane_b32 s5, v252, 17
	v_readlane_b32 s7, v252, 19
	v_readlane_b32 s12, v252, 24
	v_readlane_b32 s13, v252, 25
	v_readlane_b32 s16, v252, 28
	v_readlane_b32 s17, v252, 29
	v_readlane_b32 s18, v252, 30
	v_readlane_b32 s19, v252, 31
	s_cbranch_vccnz .Lbsh_g2_go
	s_barrier
	s_branch .LBB0_566
.Lbsh_g2_go:
	v_lshlrev_b32_e32 v0, 4, v20
	v_add_u32_e32 v2, 0x2000, v0
	v_ashrrev_i32_e32 v3, 31, v2
	v_lshrrev_b32_e32 v3, 22, v3
	v_add_u32_e32 v3, v2, v3
	v_ashrrev_i32_e32 v21, 10, v3
	v_mul_i32_i24_e32 v3, 0x400, v21
	v_sub_u32_e32 v2, v2, v3
	v_lshrrev_b32_e32 v3, 4, v2
	v_bitop3_b32 v2, v3, v2, 32 bitop3:0x6c
	v_ashrrev_i32_e32 v3, 31, v2
	v_lshrrev_b32_e32 v3, 26, v3
	v_add_u32_e32 v3, v2, v3
	v_lshlrev_b32_e32 v23, 3, v21
	v_ashrrev_i32_e32 v22, 6, v3
	v_and_b32_e32 v23, -16, v23
	v_add_u32_e32 v24, v22, v23
	v_and_b32_e32 v23, 3, v22
	s_mov_b32 s0, 0x3fffe0
	v_lshrrev_b32_e32 v25, 2, v24
	v_lshlrev_b32_e32 v26, 1, v24
	v_and_b32_e32 v3, 0xc0, v3
	v_and_or_b32 v23, v24, s0, v23
	v_and_b32_e32 v25, 4, v25
	v_and_b32_e32 v26, 24, v26
	v_sub_u32_e32 v2, v2, v3
	v_mov_b32_e32 v30, 1
	v_or3_b32 v25, v23, v25, v26
	v_lshlrev_b32_e32 v23, 5, v21
	v_ashrrev_i16_sdwa v2, v30, sext(v2) dst_sel:DWORD dst_unused:UNUSED_PAD src0_sel:DWORD src1_sel:BYTE_0
	v_and_b32_e32 v26, 32, v23
	v_bfe_i32 v23, v2, 0, 16
	v_add_lshl_u32 v3, v26, v23, 1
	v_lshl_add_u32 v2, v25, 10, v3
	v_lshl_add_u32 v190, v24, 10, v3
	v_bfe_i32 v3, v20, 27, 1
	v_lshrrev_b32_e32 v3, 22, v3
	v_add_u32_e32 v3, v0, v3
	v_and_b32_e32 v3, 0xfffffc00, v3
	v_sub_u32_e32 v0, v0, v3
	v_lshrrev_b32_e32 v3, 4, v0
	v_ashrrev_i32_e32 v25, 31, v20
	v_bitop3_b32 v0, v3, v0, 32 bitop3:0x6c
	v_lshrrev_b32_e32 v25, 26, v25
	v_ashrrev_i32_e32 v3, 31, v0
	v_add_u32_e32 v25, v20, v25
	v_lshrrev_b32_e32 v3, 26, v3
	v_ashrrev_i32_e32 v25, 6, v25
	v_add_u32_e32 v3, v0, v3
	v_lshlrev_b32_e32 v26, 3, v25
	v_ashrrev_i32_e32 v24, 6, v3
	v_and_b32_e32 v26, -16, v26
	v_add_u32_e32 v27, v24, v26
	v_and_b32_e32 v26, 3, v24
	v_lshrrev_b32_e32 v28, 2, v27
	v_lshlrev_b32_e32 v29, 1, v27
	v_and_b32_e32 v3, 0xc0, v3
	s_ashr_i32 s12, s6, 6
	v_and_or_b32 v26, v27, s0, v26
	v_and_b32_e32 v28, 4, v28
	v_and_b32_e32 v29, 24, v29
	v_sub_u32_e32 v0, v0, v3
	s_ashr_i32 s7, s6, 8
	s_lshl_b32 s72, s12, 10
	v_or3_b32 v28, v26, v28, v29
	v_lshlrev_b32_e32 v26, 5, v25
	v_ashrrev_i16_sdwa v0, v30, sext(v0) dst_sel:DWORD dst_unused:UNUSED_PAD src0_sel:DWORD src1_sel:BYTE_0
	v_readlane_b32 s0, v254, 1
	v_and_b32_e32 v29, 32, v26
	v_bfe_i32 v26, v0, 0, 16
	v_readlane_b32 s1, v254, 2
	s_add_u32 s0, s26, s0
	v_add_lshl_u32 v3, v29, v26, 1
	s_addc_u32 s1, s74, s1
	s_add_i32 s73, s72, 0
	v_lshl_add_u32 v0, v28, 10, v3
	s_add_i32 m0, s73, 0x10000
	v_readlane_b32 s4, v254, 6
	global_load_lds_dwordx4 v0, s[0:1]
	s_add_i32 m0, s73, 0x12000
	s_add_u32 s10, s0, 0x20000
	global_load_lds_dwordx4 v2, s[0:1]
	s_addc_u32 s11, s1, 0
	s_add_i32 m0, s73, 0x14000
	v_lshl_add_u32 v192, v27, 10, v3
	global_load_lds_dwordx4 v0, s[10:11]
	s_add_i32 m0, s73, 0x16000
	v_readlane_b32 s5, v254, 7
	global_load_lds_dwordx4 v2, s[10:11]
	s_barrier
	s_mov_b32 m0, s73
	s_add_i32 s75, s73, 0x2000
	s_add_i32 s94, s73, 0x4000
	s_nop 0
	global_load_lds_dwordx4 v192, s[4:5]
	s_mov_b32 m0, s75
	s_add_i32 s95, s73, 0x6000
	global_load_lds_dwordx4 v190, s[4:5]
	v_readlane_b32 s4, v254, 8
	s_mov_b32 m0, s94
	v_readlane_b32 s5, v254, 9
	s_cmp_eq_u32 s7, 1
	s_cselect_b64 s[10:11], -1, 0
	s_cmp_lg_u32 s7, 1
	s_nop 1
	global_load_lds_dwordx4 v192, s[4:5]
	s_mov_b32 m0, s95
	s_nop 0
	global_load_lds_dwordx4 v190, s[4:5]
	s_cbranch_scc1 .LBB0_549
	s_barrier
